# mLSTM output phase (m_out): the unit's q/k staging loads, gate loads and state-offset load issued together before one wait (was four serial load-wait steps)
# speedup vs baseline: 1.1353x; 1.0020x over previous
; #define LAS __attribute__((address_space(3)))
; DI float fexp(float x) { return __builtin_amdgcn_exp2f(x * LOG2E); }
; DI void phase_m_out(int wv, const ArgP a, LAS unsigned char* lds, int dry) {
;     ...
;         for (int e = tid; e < 1024; e += 512) { const int r = e >> 4, p = e & 15;
;             *(LAS u32x4*)(Qs + r * MC_QROW + p * 16) = *(const u32x4*)(QOK + (t0 + r) * 2048 + h * 128 + p * 8);
;             *(LAS u32x4*)(Ks + r * MC_QROW + p * 16) = *(const u32x4*)(QOK + (t0 + r) * 2048 + 1536 + h * 128 + p * 8); }
;         if (tid < 64) { const float mstv = MST[c * 4 + h]; const float b = GB[(size_t)h * S + t0 + tid], e = GE[(size_t)h * S + t0 + tid], pm = GPM[(size_t)h * S + t0 + tid];
;             const float m = b + fmaxf(mstv, pm); f_b[tid] = b; f_e[tid] = e; f_m[tid] = m; f_g[tid] = fexp(b + mstv - m); }
;         if (tid >= 64 && tid < 192) f_n[tid - 64] = NST[(size_t)(c * 4 + h) * 128 + tid - 64];
;     ...
;         { const bf16_t* cp = CST + ((size_t)(c * 4 + h) * 256 + 32 * w + r32) * 128 + 8 * hi;
; #pragma unroll
;           for (int ks = 0; ks < 8; ++ks) { const bf16x8 ca = *(const bf16x8*)(cp + 16 * ks);
;               const bf16x8 q0 = *(const LAS bf16x8*)(Qs + r32 * MC_QROW + (16 * ks + 8 * hi) * 2), q1 = *(const LAS bf16x8*)(Qs + (32 + r32) * MC_QROW + (16 * ks + 8 * hi) * 2);
;               acc0 = __builtin_amdgcn_mfma_f32_32x32x16_bf16(ca, q0, acc0, 0, 0, 0); acc1 = __builtin_amdgcn_mfma_f32_32x32x16_bf16(ca, q1, acc1, 0, 0, 0); } }
;         const float g0 = f_g[r32], g1 = f_g[32 + r32];
; #pragma unroll
;         for (int r = 0; r < 16; ++r) { acc0[r] *= g0; acc1[r] *= g1; }
;         { const bf16_t* vp = KVT + (size_t)(512 + h * 256 + 32 * w + r32) * S + t0 + 8 * hi;
; #pragma unroll
;           for (int ks = 0; ks < 4; ++ks) { const bf16x8 va = *(const bf16x8*)(vp + 16 * ks);
.LBB0_1606:
	s_ashr_i32 s48, s66, 2
	s_ashr_i32 s49, s48, 31
	s_and_b32 s76, s66, 3
	s_lshl_b64 s[68:69], s[48:49], 6
	s_ashr_i32 s99, s66, 31
	s_mov_b32 s98, s66
	s_lshl_b64 s[98:99], s[98:99], 16
	v_lshl_add_u64 v[188:189], v[50:51], 0, s[98:99]
	global_load_dwordx4 v[140:143], v[188:189], off
	global_load_dwordx4 v[144:147], v[188:189], off offset:32
	global_load_dwordx4 v[148:151], v[188:189], off offset:64
	global_load_dwordx4 v[152:155], v[188:189], off offset:96
	global_load_dwordx4 v[156:159], v[188:189], off offset:128
	global_load_dwordx4 v[160:163], v[188:189], off offset:160
	global_load_dwordx4 v[164:167], v[188:189], off offset:192
	global_load_dwordx4 v[168:171], v[188:189], off offset:224
	s_lshl_b32 s98, s76, 8
	v_add_u32_e32 v190, s98, v69
	v_ashrrev_i32_e32 v191, 31, v190
	v_lshlrev_b64 v[190:191], 15, v[190:191]
	v_lshl_add_u64 v[190:191], s[50:51], 0, v[190:191]
	v_lshl_add_u64 v[190:191], s[68:69], 1, v[190:191]
	v_lshl_add_u64 v[190:191], v[190:191], 0, v[36:37]
	global_load_dwordx4 v[172:175], v[190:191], off
	global_load_dwordx4 v[176:179], v[190:191], off offset:32
	global_load_dwordx4 v[180:183], v[190:191], off offset:64
	global_load_dwordx4 v[184:187], v[190:191], off offset:96
	s_and_saveexec_b64 s[48:49], s[4:5]
	s_lshl_b32 s0, s76, 8
	v_lshl_add_u64 v[0:1], v[52:53], 0, s[0:1]
	v_ashrrev_i32_e32 v12, 4, v32
	v_add_u32_e32 v2, 0x200, v32
	v_ashrrev_i32_e32 v13, 31, v12
	v_ashrrev_i32_e32 v14, 4, v2
	v_ashrrev_i32_e32 v15, 31, v14
	v_lshl_add_u64 v[24:25], s[68:69], 0, v[12:13]
	v_lshl_add_u64 v[2:3], s[68:69], 0, v[14:15]
	v_lshlrev_b64 v[24:25], 12, v[24:25]
	v_lshlrev_b64 v[2:3], 12, v[2:3]
	v_lshl_add_u64 v[24:25], v[0:1], 0, v[24:25]
	v_lshl_add_u64 v[2:3], v[0:1], 0, v[2:3]
	global_load_dwordx4 v[4:7], v[24:25], off
	global_load_dwordx4 v[8:11], v[24:25], off offset:3072
	global_load_dwordx4 v[16:19], v[2:3], off
	global_load_dwordx4 v[20:23], v[2:3], off offset:3072
	v_mad_u64_u32 v[12:13], s[78:79], v12, s72, v[48:49]
	v_mad_u64_u32 v[14:15], s[78:79], v14, s72, v[48:49]
	s_or_b64 exec, exec, s[48:49]
	s_and_saveexec_b64 s[48:49], s[6:7]
	s_ashr_i32 s67, s66, 31
	s_lshl_b64 s[70:71], s[66:67], 2
	s_add_u32 s70, s33, s70
	s_addc_u32 s71, s63, s71
	s_lshl_b32 s0, s76, 14
	s_add_u32 s78, s68, s0
	s_addc_u32 s79, s69, 0
	v_lshl_add_u64 v[0:1], s[78:79], 0, v[32:33]
	v_lshlrev_b64 v[0:1], 2, v[0:1]
	v_lshl_add_u64 v[2:3], s[56:57], 0, v[0:1]
	global_load_dword v26, v37, s[70:71]
	global_load_dword v27, v[2:3], off
	v_lshl_add_u64 v[2:3], s[52:53], 0, v[0:1]
	global_load_dword v28, v[2:3], off
	v_lshl_add_u64 v[0:1], s[54:55], 0, v[0:1]
	global_load_dword v29, v[0:1], off
	s_or_b64 exec, exec, s[48:49]
	s_and_saveexec_b64 s[48:49], s[8:9]
	s_lshl_b64 s[78:79], s[66:67], 9
	v_lshl_add_u64 v[0:1], v[38:39], 0, s[78:79]
	global_load_dword v30, v[0:1], off
	s_or_b64 exec, exec, s[48:49]
	s_and_saveexec_b64 s[48:49], s[4:5]
	s_waitcnt vmcnt(5)
	ds_write_b128 v12, v[4:7]
	ds_write_b128 v12, v[8:11] offset:17408
	ds_write_b128 v14, v[16:19]
	ds_write_b128 v14, v[20:23] offset:17408
	s_or_b64 exec, exec, s[48:49]
	s_and_saveexec_b64 s[48:49], s[6:7]
	s_waitcnt vmcnt(1)
	v_max_f32_e32 v1, v26, v26
	v_max_f32_e32 v3, v27, v27
	v_max_f32_e32 v1, v1, v3
	v_add_f32_e32 v1, v28, v1
	v_add_f32_e32 v3, v26, v28
	v_sub_f32_e32 v3, v3, v1
	v_mul_f32_e32 v3, 0x3fb8aa3b, v3
	v_exp_f32_e32 v3, v3
	s_nop 0
	ds_write2st64_b32 v43, v28, v29 offset0:172 offset1:173
	ds_write2st64_b32 v43, v1, v3 offset0:174 offset1:175
	s_or_b64 exec, exec, s[48:49]
	s_and_saveexec_b64 s[48:49], s[8:9]
	s_waitcnt vmcnt(0)
	ds_write_b32 v43, v30 offset:46080
